# grid barrier flat release only (last leader releases all per-XCD generation words), without the arrival-time invalidate
# baseline (speedup 1.0000x reference)
; __device__ __forceinline__ unsigned xb_ld(unsigned* p)              { return __hip_atomic_load(p, __ATOMIC_RELAXED, __HIP_MEMORY_SCOPE_AGENT); }
; __device__ __forceinline__ unsigned xb_add(unsigned* p, unsigned v) { return __hip_atomic_fetch_add(p, v, __ATOMIC_RELAXED, __HIP_MEMORY_SCOPE_AGENT); }
; #define XB_SPIN(cond, bar) do { unsigned _sp = 0; while (cond) { __builtin_amdgcn_s_sleep(1); \
;     if ((++_sp & 255u) == 0u) { if (xb_ld(&(bar)[XB_TMO])) break; if (_sp > XB_SPIN_CAP) { atomicAdd(&(bar)[XB_TMO], 1u); break; } } } } while (0)
; __device__ __forceinline__ void xcd_barrier(const XcdBarrier& b, int xtid) {
;     ...
;             if (og + 1u == (tg + 1u) * nx) xb_add(&bar[XB_TOPGEN], 1u);
;             else XB_SPIN(xb_ld(&bar[XB_TOPGEN]) == tg, bar);
;             __builtin_amdgcn_fence(__ATOMIC_ACQUIRE, "agent");
;             xb_add(&bar[XB_XGEN(b.x)], 1u);
;             asm volatile("s_waitcnt vmcnt(0)" ::: "memory");
.LBB0_154:
	s_or_b64 exec, exec, s[6:7]
	s_mov_b64 s[6:7], exec
	v_mbcnt_lo_u32_b32 v0, s6, 0
	v_mbcnt_hi_u32_b32 v0, s7, v0
	v_cmp_eq_u32_e32 vcc, 0, v0
	s_waitcnt vmcnt(0)
	buffer_inv sc1
	s_and_saveexec_b64 s[8:9], vcc
	s_cbranch_execz .LBB0_156
	s_bcnt1_i32_b64 s6, s[6:7]
	v_mov_b32_e32 v0, s6
	s_nop 0

; __device__ __forceinline__ unsigned xb_ld(unsigned* p)              { return __hip_atomic_load(p, __ATOMIC_RELAXED, __HIP_MEMORY_SCOPE_AGENT); }
; __device__ __forceinline__ unsigned xb_add(unsigned* p, unsigned v) { return __hip_atomic_fetch_add(p, v, __ATOMIC_RELAXED, __HIP_MEMORY_SCOPE_AGENT); }
; #define XB_SPIN(cond, bar) do { unsigned _sp = 0; while (cond) { __builtin_amdgcn_s_sleep(1); \
;     if ((++_sp & 255u) == 0u) { if (xb_ld(&(bar)[XB_TMO])) break; if (_sp > XB_SPIN_CAP) { atomicAdd(&(bar)[XB_TMO], 1u); break; } } } } while (0)
; __device__ __forceinline__ void xcd_barrier(const XcdBarrier& b, int xtid) {
;     ...
;             if (og + 1u == (tg + 1u) * nx) xb_add(&bar[XB_TOPGEN], 1u);
;             else XB_SPIN(xb_ld(&bar[XB_TOPGEN]) == tg, bar);
;             __builtin_amdgcn_fence(__ATOMIC_ACQUIRE, "agent");
;             xb_add(&bar[XB_XGEN(b.x)], 1u);
;             asm volatile("s_waitcnt vmcnt(0)" ::: "memory");
.LBB0_272:
	s_or_b64 exec, exec, s[8:9]
	s_mov_b64 s[8:9], exec
	v_mbcnt_lo_u32_b32 v0, s8, 0
	v_mbcnt_hi_u32_b32 v0, s9, v0
	v_cmp_eq_u32_e32 vcc, 0, v0
	s_waitcnt vmcnt(0)
	buffer_inv sc1
	s_and_saveexec_b64 s[10:11], vcc
	s_cbranch_execz .LBB0_274
	s_bcnt1_i32_b64 s8, s[8:9]
	v_mov_b32_e32 v0, s8
	s_nop 0

; __device__ __forceinline__ unsigned xb_ld(unsigned* p)              { return __hip_atomic_load(p, __ATOMIC_RELAXED, __HIP_MEMORY_SCOPE_AGENT); }
; __device__ __forceinline__ unsigned xb_add(unsigned* p, unsigned v) { return __hip_atomic_fetch_add(p, v, __ATOMIC_RELAXED, __HIP_MEMORY_SCOPE_AGENT); }
; #define XB_SPIN(cond, bar) do { unsigned _sp = 0; while (cond) { __builtin_amdgcn_s_sleep(1); \
;     if ((++_sp & 255u) == 0u) { if (xb_ld(&(bar)[XB_TMO])) break; if (_sp > XB_SPIN_CAP) { atomicAdd(&(bar)[XB_TMO], 1u); break; } } } } while (0)
; __device__ __forceinline__ void xcd_barrier(const XcdBarrier& b, int xtid) {
;     ...
;             if (og + 1u == (tg + 1u) * nx) xb_add(&bar[XB_TOPGEN], 1u);
;             else XB_SPIN(xb_ld(&bar[XB_TOPGEN]) == tg, bar);
;             __builtin_amdgcn_fence(__ATOMIC_ACQUIRE, "agent");
;             xb_add(&bar[XB_XGEN(b.x)], 1u);
;             asm volatile("s_waitcnt vmcnt(0)" ::: "memory");
.LBB0_475:
	s_or_b64 exec, exec, s[10:11]
	s_mov_b64 s[10:11], exec
	v_mbcnt_lo_u32_b32 v0, s10, 0
	v_mbcnt_hi_u32_b32 v0, s11, v0
	v_cmp_eq_u32_e32 vcc, 0, v0
	s_waitcnt vmcnt(0)
	buffer_inv sc1
	s_and_saveexec_b64 s[12:13], vcc
	s_cbranch_execz .LBB0_477
	s_bcnt1_i32_b64 s10, s[10:11]
	v_mov_b32_e32 v0, s10
	s_nop 0

; __device__ __forceinline__ unsigned xb_ld(unsigned* p)              { return __hip_atomic_load(p, __ATOMIC_RELAXED, __HIP_MEMORY_SCOPE_AGENT); }
; __device__ __forceinline__ unsigned xb_add(unsigned* p, unsigned v) { return __hip_atomic_fetch_add(p, v, __ATOMIC_RELAXED, __HIP_MEMORY_SCOPE_AGENT); }
; #define XB_SPIN(cond, bar) do { unsigned _sp = 0; while (cond) { __builtin_amdgcn_s_sleep(1); \
;     if ((++_sp & 255u) == 0u) { if (xb_ld(&(bar)[XB_TMO])) break; if (_sp > XB_SPIN_CAP) { atomicAdd(&(bar)[XB_TMO], 1u); break; } } } } while (0)
; __device__ __forceinline__ void xcd_barrier(const XcdBarrier& b, int xtid) {
;     ...
;             if (og + 1u == (tg + 1u) * nx) xb_add(&bar[XB_TOPGEN], 1u);
;             else XB_SPIN(xb_ld(&bar[XB_TOPGEN]) == tg, bar);
;             __builtin_amdgcn_fence(__ATOMIC_ACQUIRE, "agent");
;             xb_add(&bar[XB_XGEN(b.x)], 1u);
;             asm volatile("s_waitcnt vmcnt(0)" ::: "memory");
.LBB0_541:
	s_or_b64 exec, exec, s[12:13]
	s_mov_b64 s[12:13], exec
	v_mbcnt_lo_u32_b32 v0, s12, 0
	v_mbcnt_hi_u32_b32 v0, s13, v0
	v_cmp_eq_u32_e32 vcc, 0, v0
	s_waitcnt vmcnt(0)
	buffer_inv sc1
	s_and_saveexec_b64 s[14:15], vcc
	s_cbranch_execz .LBB0_543
	s_bcnt1_i32_b64 s12, s[12:13]
	v_mov_b32_e32 v0, s12
	s_nop 0
